# wait relaxation: MLA task-end barrier waits lgkmcnt only (store acks no longer drained before the barrier)
# baseline (speedup 1.0000x reference)
.LBB0_310:
	s_or_b64 exec, exec, s[40:41]
	v_and_b32_e32 v67, 64, v210
	v_xor_b32_e32 v66, 32, v210
	v_add_u32_e32 v67, 64, v67
	v_cmp_lt_i32_e32 vcc, v66, v67
	s_nop 1
	v_cndmask_b32_e32 v66, v210, v66, vcc
	v_lshlrev_b32_e32 v66, 2, v66
	ds_bpermute_b32 v66, v66, v233
	v_cmp_lt_u32_e32 vcc, v226, v175
	s_and_saveexec_b64 s[4:5], vcc
	s_cbranch_execz .LBB0_312
	v_readlane_b32 s6, v254, 20
	v_lshlrev_b64 v[68:69], 11, v[0:1]
	v_readlane_b32 s7, v254, 21
	s_waitcnt lgkmcnt(0)
	v_add_f32_e32 v70, v233, v66
	v_lshlrev_b32_e32 v0, 11, v226
	v_lshl_add_u64 v[68:69], s[6:7], 0, v[68:69]
	v_div_scale_f32 v71, s[6:7], v70, v70, 1.0
	v_rcp_f32_e32 v72, v71
	v_lshl_add_u64 v[68:69], v[68:69], 0, v[0:1]
	v_lshl_add_u64 v[66:67], v[176:177], 1, v[68:69]
	v_lshlrev_b32_e32 v0, 1, v179
	v_lshl_add_u64 v[66:67], v[66:67], 0, v[0:1]
	v_fma_f32 v0, -v71, v72, 1.0
	v_fmac_f32_e32 v72, v0, v72
	v_div_scale_f32 v0, vcc, 1.0, v70, 1.0
	v_mul_f32_e32 v68, v0, v72
	v_fma_f32 v69, -v71, v68, v0
	v_fmac_f32_e32 v68, v69, v72
	v_fma_f32 v0, -v71, v68, v0
	v_div_fmas_f32 v0, v0, v72, v68
	v_div_fixup_f32 v0, v0, v70, 1.0
	v_and_b32_e32 v70, 32, v210
	v_lshrrev_b32_e32 v70, 2, v70
	v_mov_b32_e32 v71, 0
	v_lshl_add_u64 v[68:69], v[66:67], 0, v[70:71]
	v_pk_mul_f32 v[34:35], v[34:35], v[0:1] op_sel_hi:[1,0]
	v_pk_mul_f32 v[36:37], v[36:37], v[0:1] op_sel_hi:[1,0]
	v_pk_mul_f32 v[38:39], v[38:39], v[0:1] op_sel_hi:[1,0]
	v_pk_mul_f32 v[40:41], v[40:41], v[0:1] op_sel_hi:[1,0]
	v_cvt_pk_bf16_f32 v34, v34, v35
	v_cvt_pk_bf16_f32 v35, v36, v37
	v_cvt_pk_bf16_f32 v36, v38, v39
	v_cvt_pk_bf16_f32 v37, v40, v41
	s_nop 1
	v_permlane32_swap_b32_e32 v34, v36
	v_permlane32_swap_b32_e32 v35, v37
	global_store_dwordx4 v[68:69], v[34:37], off
	v_pk_mul_f32 v[42:43], v[42:43], v[0:1] op_sel_hi:[1,0]
	v_pk_mul_f32 v[44:45], v[44:45], v[0:1] op_sel_hi:[1,0]
	v_pk_mul_f32 v[46:47], v[46:47], v[0:1] op_sel_hi:[1,0]
	v_pk_mul_f32 v[48:49], v[48:49], v[0:1] op_sel_hi:[1,0]
	v_cvt_pk_bf16_f32 v42, v42, v43
	v_cvt_pk_bf16_f32 v43, v44, v45
	v_cvt_pk_bf16_f32 v44, v46, v47
	v_cvt_pk_bf16_f32 v45, v48, v49
	s_nop 1
	v_permlane32_swap_b32_e32 v42, v44
	v_permlane32_swap_b32_e32 v43, v45
	global_store_dwordx4 v[68:69], v[42:45], off offset:32
	v_pk_mul_f32 v[50:51], v[50:51], v[0:1] op_sel_hi:[1,0]
	v_pk_mul_f32 v[52:53], v[52:53], v[0:1] op_sel_hi:[1,0]
	v_pk_mul_f32 v[54:55], v[54:55], v[0:1] op_sel_hi:[1,0]
	v_pk_mul_f32 v[56:57], v[56:57], v[0:1] op_sel_hi:[1,0]
	v_cvt_pk_bf16_f32 v50, v50, v51
	v_cvt_pk_bf16_f32 v51, v52, v53
	v_cvt_pk_bf16_f32 v52, v54, v55
	v_cvt_pk_bf16_f32 v53, v56, v57
	s_nop 1
	v_permlane32_swap_b32_e32 v50, v52
	v_permlane32_swap_b32_e32 v51, v53
	global_store_dwordx4 v[68:69], v[50:53], off offset:64
	v_pk_mul_f32 v[58:59], v[58:59], v[0:1] op_sel_hi:[1,0]
	v_pk_mul_f32 v[60:61], v[60:61], v[0:1] op_sel_hi:[1,0]
	v_pk_mul_f32 v[62:63], v[62:63], v[0:1] op_sel_hi:[1,0]
	v_pk_mul_f32 v[64:65], v[64:65], v[0:1] op_sel_hi:[1,0]
	v_cvt_pk_bf16_f32 v58, v58, v59
	v_cvt_pk_bf16_f32 v59, v60, v61
	v_cvt_pk_bf16_f32 v60, v62, v63
	v_cvt_pk_bf16_f32 v61, v64, v65
	s_nop 1
	v_permlane32_swap_b32_e32 v58, v60
	v_permlane32_swap_b32_e32 v59, v61
	global_store_dwordx4 v[68:69], v[58:61], off offset:96
	v_pk_mul_f32 v[18:19], v[18:19], v[0:1] op_sel_hi:[1,0]
	v_pk_mul_f32 v[20:21], v[20:21], v[0:1] op_sel_hi:[1,0]
	v_pk_mul_f32 v[22:23], v[22:23], v[0:1] op_sel_hi:[1,0]
	v_pk_mul_f32 v[24:25], v[24:25], v[0:1] op_sel_hi:[1,0]
	v_cvt_pk_bf16_f32 v18, v18, v19
	v_cvt_pk_bf16_f32 v19, v20, v21
	v_cvt_pk_bf16_f32 v20, v22, v23
	v_cvt_pk_bf16_f32 v21, v24, v25
	s_nop 1
	v_permlane32_swap_b32_e32 v18, v20
	v_permlane32_swap_b32_e32 v19, v21
	global_store_dwordx4 v[68:69], v[18:21], off offset:128
	v_pk_mul_f32 v[26:27], v[26:27], v[0:1] op_sel_hi:[1,0]
	v_pk_mul_f32 v[28:29], v[28:29], v[0:1] op_sel_hi:[1,0]
	v_pk_mul_f32 v[30:31], v[30:31], v[0:1] op_sel_hi:[1,0]
	v_pk_mul_f32 v[32:33], v[32:33], v[0:1] op_sel_hi:[1,0]
	v_cvt_pk_bf16_f32 v26, v26, v27
	v_cvt_pk_bf16_f32 v27, v28, v29
	v_cvt_pk_bf16_f32 v28, v30, v31
	v_cvt_pk_bf16_f32 v29, v32, v33
	s_nop 1
	v_permlane32_swap_b32_e32 v26, v28
	v_permlane32_swap_b32_e32 v27, v29
	global_store_dwordx4 v[68:69], v[26:29], off offset:160
	v_pk_mul_f32 v[2:3], v[2:3], v[0:1] op_sel_hi:[1,0]
	v_pk_mul_f32 v[4:5], v[4:5], v[0:1] op_sel_hi:[1,0]
	v_pk_mul_f32 v[6:7], v[6:7], v[0:1] op_sel_hi:[1,0]
	v_pk_mul_f32 v[8:9], v[8:9], v[0:1] op_sel_hi:[1,0]
	v_cvt_pk_bf16_f32 v2, v2, v3
	v_cvt_pk_bf16_f32 v3, v4, v5
	v_cvt_pk_bf16_f32 v4, v6, v7
	v_cvt_pk_bf16_f32 v5, v8, v9
	s_nop 1
	v_permlane32_swap_b32_e32 v2, v4
	v_permlane32_swap_b32_e32 v3, v5
	global_store_dwordx4 v[68:69], v[2:5], off offset:192
	v_pk_mul_f32 v[10:11], v[10:11], v[0:1] op_sel_hi:[1,0]
	v_pk_mul_f32 v[12:13], v[12:13], v[0:1] op_sel_hi:[1,0]
	v_pk_mul_f32 v[14:15], v[14:15], v[0:1] op_sel_hi:[1,0]
	v_pk_mul_f32 v[16:17], v[16:17], v[0:1] op_sel_hi:[1,0]
	v_cvt_pk_bf16_f32 v10, v10, v11
	v_cvt_pk_bf16_f32 v11, v12, v13
	v_cvt_pk_bf16_f32 v12, v14, v15
	v_cvt_pk_bf16_f32 v13, v16, v17
	s_nop 1
	v_permlane32_swap_b32_e32 v10, v12
	v_permlane32_swap_b32_e32 v11, v13
	global_store_dwordx4 v[68:69], v[10:13], off offset:224
.LBB0_312:
	s_or_b64 exec, exec, s[4:5]
	s_waitcnt lgkmcnt(0)
	s_barrier
.LBB0_313:
	v_readlane_b32 s4, v254, 56
	v_readlane_b32 s5, v254, 57
	s_or_b64 exec, exec, s[4:5]
